# work queue: attention and states items fetch the next ticket (atomic) late in the item (after the K loop / before the state MFMA loop); the next dequeue consumes it instead of issuing its own atomic
# speedup vs baseline: 1.0054x; 1.0040x over previous
.LBB0_766:
	s_or_b64 exec, exec, s[0:1]
	s_mov_b64 s[0:1], s[90:91]
	s_waitcnt lgkmcnt(0)
	s_barrier
	s_cmp_eq_u64 s[0:1], 0
	s_cbranch_scc1 .LBB0_1578
	s_load_dwordx2 s[86:87], s[0:1], 0xd0
	v_mov_b32_e32 v1, 0
	s_mov_b32 s32, 0
	v_mbcnt_lo_u32_b32 v0, -1, 0
	s_mov_b32 s80, 0x42b17218
	v_mov_b32_e32 v178, 0x3ecc95a3
	s_waitcnt lgkmcnt(0)
	s_add_u32 s26, s86, 0x23eba00
	s_addc_u32 s27, s87, 0
	s_add_u32 s12, s86, 0x22e0000
	s_addc_u32 s13, s87, 0
	s_add_u32 s2, s86, 0x23e4000
	v_writelane_b32 v254, s2, 36
	s_addc_u32 s2, s87, 0
	v_writelane_b32 v254, s2, 44
	s_add_u32 s2, s86, 0xf77e200
	s_addc_u32 s3, s87, 0
	s_add_u32 s28, s86, 0x1797e200
	s_addc_u32 s16, s87, 0
	v_writelane_b32 v254, s2, 32
	s_add_u32 s79, s86, 0xa5ee200
	s_movk_i32 s92, 0x1000
	v_writelane_b32 v254, s3, 33
	s_addc_u32 s2, s87, 0
	v_writelane_b32 v254, s2, 46
	s_add_u32 s2, s86, 0xce6e200
	v_writelane_b32 v254, s2, 48
	s_addc_u32 s2, s87, 0
	s_add_u32 s95, s86, 0x656e200
	s_addc_u32 s22, s87, 0
	s_add_u32 s23, s86, 0x1387e200
	s_addc_u32 s24, s87, 0
	v_writelane_b32 v254, s2, 50
	s_add_u32 s2, s86, 0xd6fe200
	v_writelane_b32 v254, s2, 38
	s_addc_u32 s2, s87, 0
	v_writelane_b32 v254, s2, 42
	s_add_u32 s2, s86, 0x85ee200
	v_writelane_b32 v254, s2, 34
	s_addc_u32 s2, s87, 0
	s_add_u32 s74, s86, 0x1300000
	s_addc_u32 s75, s87, 0
	s_add_u32 s14, s86, 0x880000
	s_addc_u32 s15, s87, 0
	s_add_u32 s82, s86, 0x1840000
	s_addc_u32 s83, s87, 0
	s_add_u32 s20, s86, 0x680000
	s_addc_u32 s21, s87, 0
	s_add_i32 s29, 0, 0x23fe0
	v_writelane_b32 v254, s2, 40
	s_movk_i32 s93, 0x2000
	s_movk_i32 s94, 0x3000
	s_movk_i32 s25, 0x820
	s_movk_i32 s96, 0xc0
	s_mov_b32 s97, 0xf149f2ca
	s_movk_i32 s81, 0x220
	v_mbcnt_hi_u32_b32 v179, -1, v0
	v_mov_b32_e32 v180, 0x3727c5ac
	s_mov_b32 s19, 0xf800000
	v_mov_b32_e32 v181, 0x260
	s_mov_b32 s89, 0x5040100
	s_mov_b32 s88, 0xae6e000
	s_mov_b32 s17, 0xae6f000
	v_mov_b32_e32 v182, s29
	v_mov_b32_e32 v183, 0x7f800000
	v_mov_b32_e32 v164, 0x3f317218
	v_bfrev_b32_e32 v184, 0.5
	v_mov_b32_e32 v185, 0xf149f2ca
	v_mov_b32_e32 v186, 0x80
	v_mov_b32_e32 v187, 6
	s_mov_b64 s[84:85], 0x2000
	s_mov_b64 s[90:91], 0x100
	s_mov_b64 s[34:35], 0x10000
	s_mov_b32 s77, 0
	s_branch .LBB0_770

.LBB0_770:
	s_barrier
	s_mov_b64 s[2:3], exec
	v_readlane_b32 s4, v253, 0
	v_readlane_b32 s5, v253, 1
	s_and_b64 s[4:5], s[2:3], s[4:5]
	s_mov_b64 exec, s[4:5]
	s_cbranch_execz .LBB0_774
	s_mov_b64 s[6:7], exec
	v_mbcnt_lo_u32_b32 v0, s6, 0
	v_mbcnt_hi_u32_b32 v0, s7, v0
	v_cmp_eq_u32_e32 vcc, 0, v0
	s_and_saveexec_b64 s[4:5], vcc
	s_cbranch_execz .LBB0_773
	s_cmp_eq_u32 s32, 1
	s_cbranch_scc1 .Lq_have
	s_bcnt1_i32_b64 s6, s[6:7]
	v_mov_b32_e32 v2, s6
	global_atomic_add v2, v1, v2, s[26:27] sc0
	s_branch .LBB0_773
.Lq_have:
	s_mov_b32 s32, 0
	s_waitcnt vmcnt(0)
	v_mov_b32_e32 v2, v255

.LBB0_1426:
	s_or_b64 exec, exec, s[38:39]
	s_mov_b64 s[98:99], exec
	v_readlane_b32 s100, v253, 0
	v_readlane_b32 s101, v253, 1
	s_and_b64 s[100:101], s[98:99], s[100:101]
	s_mov_b64 exec, s[100:101]
	s_cbranch_execz .Lq_pf_done_s
	v_mbcnt_lo_u32_b32 v255, s100, 0
	v_mbcnt_hi_u32_b32 v255, s101, v255
	v_cmp_eq_u32_e32 vcc, 0, v255
	s_and_b64 exec, exec, vcc
	s_bcnt1_i32_b64 s100, s[100:101]
	v_mov_b32_e32 v255, s100
	global_atomic_add v255, v1, v255, s[26:27] sc0
	s_mov_b32 s32, 1
.Lq_pf_done_s:
	s_mov_b64 exec, s[98:99]
	s_lshl_b32 s2, s9, 3
	s_add_u32 s2, s30, s2
	s_addc_u32 s3, s31, 0
	v_lshrrev_b32_e32 v4, 5, v140
	v_bfe_u32 v3, v121, 2, 2
	s_lshl_b64 s[2:3], s[2:3], 14
	v_and_b32_e32 v0, 31, v121
	v_and_b32_e32 v2, 16, v121
	s_add_u32 s2, s28, s2
	v_lshl_or_b32 v5, v4, 3, v3
	v_lshlrev_b32_e32 v3, 2, v121
	s_addc_u32 s3, s16, s3
	v_and_or_b32 v2, v3, 12, v2
	v_lshlrev_b32_e32 v0, 1, v0
	v_lshlrev_b32_e32 v6, 1, v2
	s_lshl_b32 s4, s8, 1
	v_lshl_add_u64 v[2:3], s[2:3], 0, v[0:1]
	v_mul_u32_u24_e32 v0, 0x820, v5
	s_and_b32 s4, s4, 0xffffff80
	s_and_b32 s5, s8, 0xffffff00
	v_add3_u32 v68, 0, v6, v0
	v_lshlrev_b32_e32 v0, 10, v4
	s_add_i32 s6, s5, 0x400
	s_or_b32 s7, s4, 64
	v_add_u32_e32 v69, 0x10400, v68
	v_add_u32_e32 v70, 0x12480, v68
	v_add_u32_e32 v71, 0x18600, v68
	v_add_u32_e32 v72, 0x1a680, v68
	v_lshl_add_u64 v[66:67], v[2:3], 0, v[0:1]
	s_mov_b32 s8, 0
	s_mov_b64 s[2:3], -1
	s_waitcnt lgkmcnt(0)
	s_barrier

.LBB0_1566:
	s_setprio 0
	s_mov_b64 s[98:99], exec
	v_readlane_b32 s100, v253, 0
	v_readlane_b32 s101, v253, 1
	s_and_b64 s[100:101], s[98:99], s[100:101]
	s_mov_b64 exec, s[100:101]
	s_cbranch_execz .Lq_pf_done_a
	v_mbcnt_lo_u32_b32 v255, s100, 0
	v_mbcnt_hi_u32_b32 v255, s101, v255
	v_cmp_eq_u32_e32 vcc, 0, v255
	s_and_b64 exec, exec, vcc
	s_bcnt1_i32_b64 s100, s[100:101]
	v_mov_b32_e32 v255, s100
	global_atomic_add v255, v1, v255, s[26:27] sc0
	s_mov_b32 s32, 1
.Lq_pf_done_a:
	s_mov_b64 exec, s[98:99]
	v_div_scale_f32 v67, s[2:3], v66, v66, 1.0
	v_rcp_f32_e32 v68, v67
	v_div_scale_f32 v69, vcc, 1.0, v66, 1.0
	s_lshl_b32 s2, s6, 2
	v_fma_f32 v70, -v67, v68, 1.0
	v_fmac_f32_e32 v68, v70, v68
	v_mul_f32_e32 v70, v69, v68
	v_fma_f32 v71, -v67, v70, v69
	v_fmac_f32_e32 v70, v71, v68
	v_fma_f32 v67, -v67, v70, v69
	v_div_fmas_f32 v67, v67, v68, v70
	v_div_fixup_f32 v68, v67, v66, 1.0
	v_pk_mul_f32 v[110:111], v[68:69], v[50:51] op_sel_hi:[0,1]
	v_pk_mul_f32 v[50:51], v[110:111], v[110:111]
	v_pk_mul_f32 v[112:113], v[68:69], v[52:53] op_sel_hi:[0,1]
	v_pk_mul_f32 v[52:53], v[112:113], v[112:113]
	v_add_f32_e32 v50, v50, v51
	v_pk_mul_f32 v[108:109], v[68:69], v[54:55] op_sel_hi:[0,1]
	v_add_f32_e32 v50, v52, v50
	v_pk_mul_f32 v[54:55], v[108:109], v[108:109]
	v_add_f32_e32 v50, v53, v50
	v_pk_mul_f32 v[106:107], v[68:69], v[56:57] op_sel_hi:[0,1]
	v_add_f32_e32 v50, v54, v50
	v_pk_mul_f32 v[56:57], v[106:107], v[106:107]
	v_add_f32_e32 v50, v55, v50
	v_pk_mul_f32 v[104:105], v[68:69], v[58:59] op_sel_hi:[0,1]
	v_add_f32_e32 v50, v56, v50
	v_pk_mul_f32 v[58:59], v[104:105], v[104:105]
	v_add_f32_e32 v50, v57, v50
	v_pk_mul_f32 v[102:103], v[68:69], v[60:61] op_sel_hi:[0,1]
	v_add_f32_e32 v50, v58, v50
	v_pk_mul_f32 v[60:61], v[102:103], v[102:103]
	v_add_f32_e32 v50, v59, v50
	v_pk_mul_f32 v[84:85], v[68:69], v[62:63] op_sel_hi:[0,1]
	v_add_f32_e32 v50, v60, v50
	v_pk_mul_f32 v[62:63], v[84:85], v[84:85]
	v_add_f32_e32 v50, v61, v50
	v_pk_mul_f32 v[82:83], v[68:69], v[64:65] op_sel_hi:[0,1]
	v_add_f32_e32 v50, v62, v50
	v_pk_mul_f32 v[64:65], v[82:83], v[82:83]
	v_add_f32_e32 v50, v63, v50
	v_pk_mul_f32 v[80:81], v[68:69], v[34:35] op_sel_hi:[0,1]
	v_add_f32_e32 v50, v64, v50
	v_pk_mul_f32 v[34:35], v[80:81], v[80:81]
	v_add_f32_e32 v50, v65, v50
	v_pk_mul_f32 v[78:79], v[68:69], v[36:37] op_sel_hi:[0,1]
	v_add_f32_e32 v34, v34, v50
	v_pk_mul_f32 v[36:37], v[78:79], v[78:79]
	v_add_f32_e32 v34, v35, v34
	v_pk_mul_f32 v[76:77], v[68:69], v[38:39] op_sel_hi:[0,1]
	v_add_f32_e32 v34, v36, v34
	v_pk_mul_f32 v[38:39], v[76:77], v[76:77]
	v_add_f32_e32 v34, v37, v34
	v_pk_mul_f32 v[74:75], v[68:69], v[40:41] op_sel_hi:[0,1]
	v_add_f32_e32 v34, v38, v34
	v_pk_mul_f32 v[40:41], v[74:75], v[74:75]
	v_add_f32_e32 v34, v39, v34
	v_pk_mul_f32 v[72:73], v[68:69], v[42:43] op_sel_hi:[0,1]
	v_add_f32_e32 v34, v40, v34
	v_pk_mul_f32 v[42:43], v[72:73], v[72:73]
	v_add_f32_e32 v34, v41, v34
	v_pk_mul_f32 v[70:71], v[68:69], v[44:45] op_sel_hi:[0,1]
	v_add_f32_e32 v34, v42, v34
	v_pk_mul_f32 v[44:45], v[70:71], v[70:71]
	v_add_f32_e32 v34, v43, v34
	v_pk_mul_f32 v[66:67], v[68:69], v[46:47] op_sel_hi:[0,1]
	v_add_f32_e32 v34, v44, v34
	v_pk_mul_f32 v[46:47], v[66:67], v[66:67]
	v_add_f32_e32 v34, v45, v34
	v_pk_mul_f32 v[68:69], v[68:69], v[48:49] op_sel_hi:[0,1]
	v_add_f32_e32 v34, v46, v34
	v_pk_mul_f32 v[48:49], v[68:69], v[68:69]
	v_add_f32_e32 v34, v47, v34
	v_add_f32_e32 v34, v48, v34
	v_add_f32_e32 v34, v49, v34
	ds_bpermute_b32 v35, v99, v34
	s_add_i32 s2, s2, 0
	v_cmp_gt_u32_e64 s[40:41], 32, v173
	v_lshl_add_u32 v87, v172, 2, s2
	s_and_saveexec_b64 s[2:3], s[40:41]
	s_cbranch_execz .LBB0_1568
	s_waitcnt lgkmcnt(0)
	v_add_f32_e32 v34, v34, v35
	ds_write_b32 v87, v34 offset:8320
